# GEMM K-loop: LDS fragment reads rebalanced 12/4/8/0 -> 8/4/8/4 (next K-tile B0 prefetched in phases 4/8, extra counted vmcnt(6) in phases 2/6)
# speedup vs baseline: 1.0136x; 1.0136x over previous
.LBB0_385:
	s_add_i32 s43, s6, -2
	s_add_u32 s0, s46, 0x80
	s_addc_u32 s1, s47, 0
	s_add_u32 s48, s44, 0x100
	v_mov_b32_e32 v2, 0
	s_addc_u32 s49, s45, 0
	s_mov_b32 s44, 0
	v_mov_b32_e32 v3, v2
	v_mov_b32_e32 v4, v2
	v_mov_b32_e32 v5, v2
	v_mov_b32_e32 v6, v2
	v_mov_b32_e32 v7, v2
	v_mov_b32_e32 v8, v2
	v_mov_b32_e32 v9, v2
	s_waitcnt vmcnt(0)
	v_mov_b32_e32 v18, v2
	v_mov_b32_e32 v19, v2
	v_mov_b32_e32 v20, v2
	v_mov_b32_e32 v21, v2
	v_mov_b32_e32 v22, v2
	v_mov_b32_e32 v23, v2
	v_mov_b32_e32 v24, v2
	v_mov_b32_e32 v25, v2
	v_mov_b32_e32 v34, v2
	v_mov_b32_e32 v35, v2
	v_mov_b32_e32 v36, v2
	v_mov_b32_e32 v37, v2
	v_mov_b32_e32 v38, v2
	v_mov_b32_e32 v39, v2
	v_mov_b32_e32 v40, v2
	v_mov_b32_e32 v41, v2
	v_mov_b32_e32 v50, v2
	v_mov_b32_e32 v51, v2
	v_mov_b32_e32 v52, v2
	v_mov_b32_e32 v53, v2
	v_mov_b32_e32 v54, v2
	v_mov_b32_e32 v55, v2
	v_mov_b32_e32 v56, v2
	v_mov_b32_e32 v57, v2
	v_mov_b32_e32 v10, v2
	v_mov_b32_e32 v11, v2
	v_mov_b32_e32 v12, v2
	v_mov_b32_e32 v13, v2
	v_mov_b32_e32 v14, v2
	v_mov_b32_e32 v15, v2
	v_mov_b32_e32 v16, v2
	v_mov_b32_e32 v17, v2
	v_mov_b32_e32 v26, v2
	v_mov_b32_e32 v27, v2
	v_mov_b32_e32 v28, v2
	v_mov_b32_e32 v29, v2
	v_mov_b32_e32 v30, v2
	v_mov_b32_e32 v31, v2
	v_mov_b32_e32 v32, v2
	v_mov_b32_e32 v33, v2
	v_mov_b32_e32 v42, v2
	v_mov_b32_e32 v43, v2
	v_mov_b32_e32 v44, v2
	v_mov_b32_e32 v45, v2
	v_mov_b32_e32 v46, v2
	v_mov_b32_e32 v47, v2
	v_mov_b32_e32 v48, v2
	v_mov_b32_e32 v49, v2
	v_mov_b32_e32 v58, v2
	v_mov_b32_e32 v59, v2
	v_mov_b32_e32 v60, v2
	v_mov_b32_e32 v61, v2
	v_mov_b32_e32 v62, v2
	v_mov_b32_e32 v63, v2
	v_mov_b32_e32 v64, v2
	v_mov_b32_e32 v65, v2
	v_mov_b32_e32 v66, v2
	v_mov_b32_e32 v67, v2
	v_mov_b32_e32 v68, v2
	v_mov_b32_e32 v69, v2
	v_mov_b32_e32 v70, v2
	v_mov_b32_e32 v71, v2
	v_mov_b32_e32 v72, v2
	v_mov_b32_e32 v73, v2
	v_mov_b32_e32 v82, v2
	v_mov_b32_e32 v83, v2
	s_waitcnt vmcnt(0)
	v_mov_b32_e32 v84, v2
	v_mov_b32_e32 v85, v2
	v_mov_b32_e32 v86, v2
	v_mov_b32_e32 v87, v2
	v_mov_b32_e32 v88, v2
	v_mov_b32_e32 v89, v2
	v_mov_b32_e32 v98, v2
	v_mov_b32_e32 v99, v2
	v_mov_b32_e32 v100, v2
	v_mov_b32_e32 v101, v2
	v_mov_b32_e32 v102, v2
	v_mov_b32_e32 v103, v2
	v_mov_b32_e32 v104, v2
	v_mov_b32_e32 v105, v2
	v_mov_b32_e32 v114, v2
	v_mov_b32_e32 v115, v2
	v_mov_b32_e32 v116, v2
	v_mov_b32_e32 v117, v2
	v_mov_b32_e32 v118, v2
	v_mov_b32_e32 v119, v2
	v_mov_b32_e32 v120, v2
	v_mov_b32_e32 v121, v2
	v_mov_b32_e32 v74, v2
	v_mov_b32_e32 v75, v2
	v_mov_b32_e32 v76, v2
	v_mov_b32_e32 v77, v2
	v_mov_b32_e32 v78, v2
	v_mov_b32_e32 v79, v2
	v_mov_b32_e32 v80, v2
	v_mov_b32_e32 v81, v2
	v_mov_b32_e32 v90, v2
	v_mov_b32_e32 v91, v2
	v_mov_b32_e32 v92, v2
	v_mov_b32_e32 v93, v2
	v_mov_b32_e32 v94, v2
	v_mov_b32_e32 v95, v2
	v_mov_b32_e32 v96, v2
	v_mov_b32_e32 v97, v2
	v_mov_b32_e32 v106, v2
	v_mov_b32_e32 v107, v2
	v_mov_b32_e32 v108, v2
	v_mov_b32_e32 v109, v2
	v_mov_b32_e32 v110, v2
	v_mov_b32_e32 v111, v2
	v_mov_b32_e32 v112, v2
	v_mov_b32_e32 v113, v2
	v_mov_b32_e32 v122, v2
	v_mov_b32_e32 v123, v2
	v_mov_b32_e32 v124, v2
	v_mov_b32_e32 v125, v2
	v_mov_b32_e32 v126, v2
	v_mov_b32_e32 v127, v2
	v_mov_b32_e32 v128, v2
	v_mov_b32_e32 v129, v2
	s_waitcnt lgkmcnt(0)
	v_add_u32_e32 v0, 0x10000, v224
	ds_read_b128 v[130:133], v0
	ds_read_b128 v[134:137], v0 offset:1024
	ds_read_b128 v[138:141], v0 offset:2048
	ds_read_b128 v[142:145], v0 offset:3072
.LBB0_386:
	s_add_i32 s71, s44, 2
	s_add_u32 s46, s0, 0x80
	s_addc_u32 s45, s1, 0
	s_add_i32 vcc_lo, 0, 0x10000
	s_cmp_eq_u32 s43, s44
	s_cselect_b32 s44, s72, s46
	s_cselect_b32 s45, s73, s45
	s_cselect_b32 s47, s75, s49
	s_cselect_b32 s46, s74, s48
	v_lshl_add_u64 v[200:201], s[0:1], 0, v[172:173]
	s_add_i32 m0, s98, 0xc000
	ds_read_b128 v[146:149], v229
	ds_read_b128 v[150:153], v229 offset:1024
	ds_read_b128 v[176:179], v229 offset:2048
	ds_read_b128 v[180:183], v229 offset:3072
	ds_read_b128 v[184:187], v229 offset:4096
	ds_read_b128 v[188:191], v229 offset:5120
	ds_read_b128 v[192:195], v229 offset:6144
	ds_read_b128 v[196:199], v229 offset:7168
	global_load_lds_dwordx4 v[200:201], off
	s_add_i32 m0, s98, 0xe000
	v_lshl_add_u64 v[200:201], s[0:1], 0, v[174:175]
	global_load_lds_dwordx4 v[200:201], off
	s_waitcnt lgkmcnt(8)
	s_barrier
	s_waitcnt lgkmcnt(0)
	v_mfma_f32_16x16x32_bf16 v[126:129], v[130:133], v[146:149], v[126:129]
	v_mfma_f32_16x16x32_bf16 v[122:125], v[138:141], v[146:149], v[122:125]
	v_mfma_f32_16x16x32_bf16 v[110:113], v[130:133], v[176:179], v[110:113]
	v_mfma_f32_16x16x32_bf16 v[106:109], v[138:141], v[176:179], v[106:109]
	v_mfma_f32_16x16x32_bf16 v[94:97], v[130:133], v[184:187], v[94:97]
	v_mfma_f32_16x16x32_bf16 v[90:93], v[138:141], v[184:187], v[90:93]
	v_mfma_f32_16x16x32_bf16 v[78:81], v[130:133], v[192:195], v[78:81]
	v_mfma_f32_16x16x32_bf16 v[74:77], v[138:141], v[192:195], v[74:77]
	v_mfma_f32_16x16x32_bf16 v[126:129], v[134:137], v[150:153], v[126:129]
	v_mfma_f32_16x16x32_bf16 v[122:125], v[142:145], v[150:153], v[122:125]
	v_mfma_f32_16x16x32_bf16 v[110:113], v[134:137], v[180:183], v[110:113]
	v_mfma_f32_16x16x32_bf16 v[106:109], v[142:145], v[180:183], v[106:109]
	v_mfma_f32_16x16x32_bf16 v[94:97], v[134:137], v[188:191], v[94:97]
	v_mfma_f32_16x16x32_bf16 v[90:93], v[142:145], v[188:191], v[90:93]
	v_mfma_f32_16x16x32_bf16 v[78:81], v[134:137], v[196:199], v[78:81]
	v_mfma_f32_16x16x32_bf16 v[74:77], v[142:145], v[196:199], v[74:77]
	s_barrier
	s_add_i32 vcc_hi, 0, 0x14000
	s_add_i32 vcc_lo, vcc_lo, s97
	v_add_u32_e32 v0, vcc_hi, v224
	v_lshl_add_u64 v[204:205], s[46:47], 0, v[158:159]
	s_mov_b32 m0, vcc_lo
	ds_read_b128 v[200:203], v0
	ds_read_b128 v[230:233], v0 offset:1024
	ds_read_b128 v[234:237], v0 offset:2048
	ds_read_b128 v[238:241], v0 offset:3072
	global_load_lds_dwordx4 v[204:205], off
	s_add_i32 m0, vcc_lo, 0x2000
	v_lshl_add_u64 v[242:243], s[46:47], 0, v[162:163]
	global_load_lds_dwordx4 v[242:243], off
	s_waitcnt vmcnt(6)
	s_barrier
	s_waitcnt lgkmcnt(0)
	v_mfma_f32_16x16x32_bf16 v[118:121], v[200:203], v[146:149], v[118:121]
	v_mfma_f32_16x16x32_bf16 v[114:117], v[234:237], v[146:149], v[114:117]
	v_mfma_f32_16x16x32_bf16 v[102:105], v[200:203], v[176:179], v[102:105]
	v_mfma_f32_16x16x32_bf16 v[98:101], v[234:237], v[176:179], v[98:101]
	v_mfma_f32_16x16x32_bf16 v[86:89], v[200:203], v[184:187], v[86:89]
	v_mfma_f32_16x16x32_bf16 v[82:85], v[234:237], v[184:187], v[82:85]
	v_mfma_f32_16x16x32_bf16 v[70:73], v[200:203], v[192:195], v[70:73]
	v_mfma_f32_16x16x32_bf16 v[66:69], v[234:237], v[192:195], v[66:69]
	v_mfma_f32_16x16x32_bf16 v[118:121], v[230:233], v[150:153], v[118:121]
	v_mfma_f32_16x16x32_bf16 v[114:117], v[238:241], v[150:153], v[114:117]
	v_mfma_f32_16x16x32_bf16 v[102:105], v[230:233], v[180:183], v[102:105]
	v_mfma_f32_16x16x32_bf16 v[98:101], v[238:241], v[180:183], v[98:101]
	v_mfma_f32_16x16x32_bf16 v[86:89], v[230:233], v[188:191], v[86:89]
	v_mfma_f32_16x16x32_bf16 v[82:85], v[238:241], v[188:191], v[82:85]
	v_mfma_f32_16x16x32_bf16 v[70:73], v[230:233], v[196:199], v[70:73]
	v_mfma_f32_16x16x32_bf16 v[66:69], v[238:241], v[196:199], v[66:69]
	s_barrier
	s_mov_b32 m0, s98
	v_lshl_add_u64 v[244:245], s[44:45], 0, v[156:157]
	ds_read_b128 v[146:149], v229 offset:16384
	ds_read_b128 v[150:153], v229 offset:17408
	ds_read_b128 v[176:179], v229 offset:18432
	ds_read_b128 v[180:183], v229 offset:19456
	ds_read_b128 v[184:187], v229 offset:20480
	ds_read_b128 v[188:191], v229 offset:21504
	ds_read_b128 v[192:195], v229 offset:22528
	ds_read_b128 v[196:199], v229 offset:23552
	global_load_lds_dwordx4 v[244:245], off
	s_mov_b32 m0, s99
	v_lshl_add_u64 v[246:247], s[44:45], 0, v[160:161]
	global_load_lds_dwordx4 v[246:247], off
	s_barrier
	s_waitcnt lgkmcnt(0)
	v_mfma_f32_16x16x32_bf16 v[62:65], v[130:133], v[146:149], v[62:65]
	v_mfma_f32_16x16x32_bf16 v[58:61], v[138:141], v[146:149], v[58:61]
	v_mfma_f32_16x16x32_bf16 v[46:49], v[130:133], v[176:179], v[46:49]
	v_mfma_f32_16x16x32_bf16 v[42:45], v[138:141], v[176:179], v[42:45]
	v_mfma_f32_16x16x32_bf16 v[30:33], v[130:133], v[184:187], v[30:33]
	v_mfma_f32_16x16x32_bf16 v[26:29], v[138:141], v[184:187], v[26:29]
	v_mfma_f32_16x16x32_bf16 v[14:17], v[130:133], v[192:195], v[14:17]
	v_mfma_f32_16x16x32_bf16 v[10:13], v[138:141], v[192:195], v[10:13]
	v_mfma_f32_16x16x32_bf16 v[62:65], v[134:137], v[150:153], v[62:65]
	v_mfma_f32_16x16x32_bf16 v[58:61], v[142:145], v[150:153], v[58:61]
	v_mfma_f32_16x16x32_bf16 v[46:49], v[134:137], v[180:183], v[46:49]
	v_mfma_f32_16x16x32_bf16 v[42:45], v[142:145], v[180:183], v[42:45]
	v_mfma_f32_16x16x32_bf16 v[30:33], v[134:137], v[188:191], v[30:33]
	v_mfma_f32_16x16x32_bf16 v[26:29], v[142:145], v[188:191], v[26:29]
	v_mfma_f32_16x16x32_bf16 v[14:17], v[134:137], v[196:199], v[14:17]
	v_mfma_f32_16x16x32_bf16 v[10:13], v[142:145], v[196:199], v[10:13]
	s_barrier
	s_add_u32 s46, s46, s95
	s_addc_u32 s47, s47, 0
	s_add_i32 vcc_lo, vcc_hi, s97
	v_lshl_add_u64 v[248:249], s[46:47], 0, v[158:159]
	s_mov_b32 m0, vcc_lo
	v_lshl_add_u64 v[250:251], s[46:47], 0, v[162:163]
	global_load_lds_dwordx4 v[248:249], off
	s_add_i32 m0, vcc_lo, 0x2000
	s_nop 0
	global_load_lds_dwordx4 v[250:251], off
	v_add_u32_e32 v0, 0x18000, v224
	ds_read_b128 v[130:133], v0
	ds_read_b128 v[134:137], v0 offset:1024
	ds_read_b128 v[138:141], v0 offset:2048
	ds_read_b128 v[142:145], v0 offset:3072
	s_waitcnt vmcnt(6)
	s_barrier
	v_mfma_f32_16x16x32_bf16 v[54:57], v[200:203], v[146:149], v[54:57]
	v_mfma_f32_16x16x32_bf16 v[50:53], v[234:237], v[146:149], v[50:53]
	v_mfma_f32_16x16x32_bf16 v[38:41], v[200:203], v[176:179], v[38:41]
	v_mfma_f32_16x16x32_bf16 v[34:37], v[234:237], v[176:179], v[34:37]
	v_mfma_f32_16x16x32_bf16 v[22:25], v[200:203], v[184:187], v[22:25]
	v_mfma_f32_16x16x32_bf16 v[18:21], v[234:237], v[184:187], v[18:21]
	v_mfma_f32_16x16x32_bf16 v[6:9], v[200:203], v[192:195], v[6:9]
	v_mfma_f32_16x16x32_bf16 v[2:5], v[234:237], v[192:195], v[2:5]
	v_mfma_f32_16x16x32_bf16 v[54:57], v[230:233], v[150:153], v[54:57]
	v_mfma_f32_16x16x32_bf16 v[50:53], v[238:241], v[150:153], v[50:53]
	v_mfma_f32_16x16x32_bf16 v[38:41], v[230:233], v[180:183], v[38:41]
	v_mfma_f32_16x16x32_bf16 v[34:37], v[238:241], v[180:183], v[34:37]
	v_mfma_f32_16x16x32_bf16 v[22:25], v[230:233], v[188:191], v[22:25]
	v_mfma_f32_16x16x32_bf16 v[18:21], v[238:241], v[188:191], v[18:21]
	v_mfma_f32_16x16x32_bf16 v[6:9], v[230:233], v[196:199], v[6:9]
	v_mfma_f32_16x16x32_bf16 v[2:5], v[238:241], v[196:199], v[2:5]
	s_barrier
	s_add_i32 s46, 0, 0x18000
	s_add_u32 s44, s44, s20
	s_addc_u32 s45, s45, 0
	s_mov_b32 m0, s94
	v_lshl_add_u64 v[200:201], s[44:45], 0, v[156:157]
	ds_read_b128 v[146:149], v229 offset:32768
	ds_read_b128 v[150:153], v229 offset:33792
	ds_read_b128 v[176:179], v229 offset:34816
	ds_read_b128 v[180:183], v229 offset:35840
	ds_read_b128 v[184:187], v229 offset:36864
	ds_read_b128 v[188:191], v229 offset:37888
	ds_read_b128 v[192:195], v229 offset:38912
	ds_read_b128 v[196:199], v229 offset:39936
	global_load_lds_dwordx4 v[200:201], off
	s_mov_b32 m0, s65
	v_lshl_add_u64 v[200:201], s[44:45], 0, v[160:161]
	global_load_lds_dwordx4 v[200:201], off
	s_waitcnt lgkmcnt(8)
	s_barrier
	s_waitcnt lgkmcnt(0)
	v_mfma_f32_16x16x32_bf16 v[126:129], v[130:133], v[146:149], v[126:129]
	v_mfma_f32_16x16x32_bf16 v[122:125], v[138:141], v[146:149], v[122:125]
	v_mfma_f32_16x16x32_bf16 v[110:113], v[130:133], v[176:179], v[110:113]
	v_mfma_f32_16x16x32_bf16 v[106:109], v[138:141], v[176:179], v[106:109]
	v_mfma_f32_16x16x32_bf16 v[94:97], v[130:133], v[184:187], v[94:97]
	v_mfma_f32_16x16x32_bf16 v[90:93], v[138:141], v[184:187], v[90:93]
	v_mfma_f32_16x16x32_bf16 v[78:81], v[130:133], v[192:195], v[78:81]
	v_mfma_f32_16x16x32_bf16 v[74:77], v[138:141], v[192:195], v[74:77]
	v_mfma_f32_16x16x32_bf16 v[126:129], v[134:137], v[150:153], v[126:129]
	v_mfma_f32_16x16x32_bf16 v[122:125], v[142:145], v[150:153], v[122:125]
	v_mfma_f32_16x16x32_bf16 v[110:113], v[134:137], v[180:183], v[110:113]
	v_mfma_f32_16x16x32_bf16 v[106:109], v[142:145], v[180:183], v[106:109]
	v_mfma_f32_16x16x32_bf16 v[94:97], v[134:137], v[188:191], v[94:97]
	v_mfma_f32_16x16x32_bf16 v[90:93], v[142:145], v[188:191], v[90:93]
	v_mfma_f32_16x16x32_bf16 v[78:81], v[134:137], v[196:199], v[78:81]
	v_mfma_f32_16x16x32_bf16 v[74:77], v[142:145], v[196:199], v[74:77]
	s_barrier
	s_add_i32 s44, 0, 0x1c000
	s_add_i32 s45, s46, s97
	v_add_u32_e32 v0, s44, v224
	v_lshl_add_u64 v[204:205], v[204:205], 0, s[22:23]
	s_mov_b32 m0, s45
	ds_read_b128 v[200:203], v0
	ds_read_b128 v[230:233], v0 offset:1024
	ds_read_b128 v[234:237], v0 offset:2048
	ds_read_b128 v[238:241], v0 offset:3072
	global_load_lds_dwordx4 v[204:205], off
	s_add_i32 m0, s45, 0x2000
	v_lshl_add_u64 v[204:205], v[242:243], 0, s[22:23]
	global_load_lds_dwordx4 v[204:205], off
	s_waitcnt vmcnt(6)
	s_barrier
	s_waitcnt lgkmcnt(0)
	v_mfma_f32_16x16x32_bf16 v[118:121], v[200:203], v[146:149], v[118:121]
	v_mfma_f32_16x16x32_bf16 v[114:117], v[234:237], v[146:149], v[114:117]
	v_mfma_f32_16x16x32_bf16 v[102:105], v[200:203], v[176:179], v[102:105]
	v_mfma_f32_16x16x32_bf16 v[98:101], v[234:237], v[176:179], v[98:101]
	v_mfma_f32_16x16x32_bf16 v[86:89], v[200:203], v[184:187], v[86:89]
	v_mfma_f32_16x16x32_bf16 v[82:85], v[234:237], v[184:187], v[82:85]
	v_mfma_f32_16x16x32_bf16 v[70:73], v[200:203], v[192:195], v[70:73]
	v_mfma_f32_16x16x32_bf16 v[66:69], v[234:237], v[192:195], v[66:69]
	v_mfma_f32_16x16x32_bf16 v[118:121], v[230:233], v[150:153], v[118:121]
	v_mfma_f32_16x16x32_bf16 v[114:117], v[238:241], v[150:153], v[114:117]
	v_mfma_f32_16x16x32_bf16 v[102:105], v[230:233], v[180:183], v[102:105]
	v_mfma_f32_16x16x32_bf16 v[98:101], v[238:241], v[180:183], v[98:101]
	v_mfma_f32_16x16x32_bf16 v[86:89], v[230:233], v[188:191], v[86:89]
	v_mfma_f32_16x16x32_bf16 v[82:85], v[238:241], v[188:191], v[82:85]
	v_mfma_f32_16x16x32_bf16 v[70:73], v[230:233], v[196:199], v[70:73]
	v_mfma_f32_16x16x32_bf16 v[66:69], v[238:241], v[196:199], v[66:69]
	s_barrier
	s_mov_b32 m0, s87
	v_lshl_add_u64 v[204:205], v[244:245], 0, s[22:23]
	ds_read_b128 v[146:149], v229 offset:49152
	ds_read_b128 v[150:153], v229 offset:50176
	ds_read_b128 v[176:179], v229 offset:51200
	ds_read_b128 v[180:183], v229 offset:52224
	ds_read_b128 v[184:187], v229 offset:53248
	ds_read_b128 v[188:191], v229 offset:54272
	ds_read_b128 v[192:195], v229 offset:55296
	ds_read_b128 v[196:199], v229 offset:56320
	global_load_lds_dwordx4 v[204:205], off
	s_mov_b32 m0, s29
	v_lshl_add_u64 v[204:205], v[246:247], 0, s[22:23]
	global_load_lds_dwordx4 v[204:205], off
	s_barrier
	s_waitcnt lgkmcnt(0)
	v_mfma_f32_16x16x32_bf16 v[62:65], v[130:133], v[146:149], v[62:65]
	v_mfma_f32_16x16x32_bf16 v[58:61], v[138:141], v[146:149], v[58:61]
	v_mfma_f32_16x16x32_bf16 v[46:49], v[130:133], v[176:179], v[46:49]
	v_mfma_f32_16x16x32_bf16 v[42:45], v[138:141], v[176:179], v[42:45]
	v_mfma_f32_16x16x32_bf16 v[30:33], v[130:133], v[184:187], v[30:33]
	v_mfma_f32_16x16x32_bf16 v[26:29], v[138:141], v[184:187], v[26:29]
	v_mfma_f32_16x16x32_bf16 v[14:17], v[130:133], v[192:195], v[14:17]
	v_mfma_f32_16x16x32_bf16 v[10:13], v[138:141], v[192:195], v[10:13]
	v_mfma_f32_16x16x32_bf16 v[62:65], v[134:137], v[150:153], v[62:65]
	v_mfma_f32_16x16x32_bf16 v[58:61], v[142:145], v[150:153], v[58:61]
	v_mfma_f32_16x16x32_bf16 v[46:49], v[134:137], v[180:183], v[46:49]
	v_mfma_f32_16x16x32_bf16 v[42:45], v[142:145], v[180:183], v[42:45]
	v_mfma_f32_16x16x32_bf16 v[30:33], v[134:137], v[188:191], v[30:33]
	v_mfma_f32_16x16x32_bf16 v[26:29], v[142:145], v[188:191], v[26:29]
	v_mfma_f32_16x16x32_bf16 v[14:17], v[134:137], v[196:199], v[14:17]
	v_mfma_f32_16x16x32_bf16 v[10:13], v[142:145], v[196:199], v[10:13]
	s_barrier
	s_add_i32 s44, s44, s97
	s_mov_b32 m0, s44
	v_lshl_add_u64 v[130:131], v[248:249], 0, s[22:23]
	global_load_lds_dwordx4 v[130:131], off
	s_add_i32 m0, s44, 0x2000
	v_lshl_add_u64 v[130:131], v[250:251], 0, s[22:23]
	global_load_lds_dwordx4 v[130:131], off
	v_add_u32_e32 v0, 0x10000, v224
	ds_read_b128 v[130:133], v0
	ds_read_b128 v[134:137], v0 offset:1024
	ds_read_b128 v[138:141], v0 offset:2048
	ds_read_b128 v[142:145], v0 offset:3072
	s_add_u32 s0, s0, 0x100
	s_addc_u32 s1, s1, 0
	s_add_u32 s48, s48, 0x100
	s_addc_u32 s49, s49, 0
	s_cmp_ge_i32 s71, s6
	s_mov_b32 s44, s71
	s_waitcnt vmcnt(6)
	s_barrier
	v_mfma_f32_16x16x32_bf16 v[54:57], v[200:203], v[146:149], v[54:57]
	v_mfma_f32_16x16x32_bf16 v[50:53], v[234:237], v[146:149], v[50:53]
	v_mfma_f32_16x16x32_bf16 v[38:41], v[200:203], v[176:179], v[38:41]
	v_mfma_f32_16x16x32_bf16 v[34:37], v[234:237], v[176:179], v[34:37]
	v_mfma_f32_16x16x32_bf16 v[22:25], v[200:203], v[184:187], v[22:25]
	v_mfma_f32_16x16x32_bf16 v[18:21], v[234:237], v[184:187], v[18:21]
	v_mfma_f32_16x16x32_bf16 v[6:9], v[200:203], v[192:195], v[6:9]
	v_mfma_f32_16x16x32_bf16 v[2:5], v[234:237], v[192:195], v[2:5]
	v_mfma_f32_16x16x32_bf16 v[54:57], v[230:233], v[150:153], v[54:57]
	v_mfma_f32_16x16x32_bf16 v[50:53], v[238:241], v[150:153], v[50:53]
	v_mfma_f32_16x16x32_bf16 v[38:41], v[230:233], v[180:183], v[38:41]
	v_mfma_f32_16x16x32_bf16 v[34:37], v[238:241], v[180:183], v[34:37]
	v_mfma_f32_16x16x32_bf16 v[22:25], v[230:233], v[188:191], v[22:25]
	v_mfma_f32_16x16x32_bf16 v[18:21], v[238:241], v[188:191], v[18:21]
	v_mfma_f32_16x16x32_bf16 v[6:9], v[230:233], v[196:199], v[6:9]
	v_mfma_f32_16x16x32_bf16 v[2:5], v[238:241], v[196:199], v[2:5]
	s_barrier
	s_cbranch_scc0 .LBB0_386
	s_lshl_b32 s46, s77, 8
	s_cmp_lt_i32 s64, 1
	s_mov_b64 s[0:1], -1
	s_cbranch_scc1 .LBB0_403
